# grid barrier: each workgroup's L1 invalidate issued at arrival (leader: with its L2 write-back) instead of after the release; nothing but L1-bypassing polls runs in between
# baseline (speedup 1.0000x reference)
.LBB0_217:
	s_lshl_b32 s1, s1, 8
	s_add_u32 s1, s38, s1
	s_addc_u32 s4, s39, 0
	v_mov_b32_e32 v1, s1
	v_add_co_u32_e32 v4, vcc, 0x2000, v1
	v_mov_b32_e32 v1, s4
	s_nop 0
	v_addc_co_u32_e32 v5, vcc, 0, v1, vcc
	v_mov_b32_e32 v1, 1
	flat_atomic_add v1, v[4:5], v1 offset:1024 sc0
	v_cvt_f32_u32_e32 v3, v2
	v_sub_u32_e32 v4, 0, v2
	s_add_u32 s3, s1, 0x1000
	s_addc_u32 s1, s4, 0
	v_rcp_iflag_f32_e32 v3, v3
	s_nop 0
	v_mul_f32_e32 v3, 0x4f7ffffe, v3
	v_cvt_u32_f32_e32 v3, v3
	v_mul_lo_u32 v4, v4, v3
	v_mul_hi_u32 v4, v3, v4
	v_add_u32_e32 v3, v3, v4
	s_waitcnt vmcnt(0) lgkmcnt(0)
	v_mul_hi_u32 v3, v1, v3
	v_mul_lo_u32 v5, v3, v2
	v_add_u32_e32 v4, 1, v1
	v_sub_u32_e32 v1, v1, v5
	v_add_u32_e32 v6, 1, v3
	v_cmp_ge_u32_e32 vcc, v1, v2
	v_sub_u32_e32 v5, v1, v2
	s_nop 0
	v_cndmask_b32_e32 v3, v3, v6, vcc
	v_cndmask_b32_e32 v1, v1, v5, vcc
	v_add_u32_e32 v5, 1, v3
	v_cmp_ge_u32_e32 vcc, v1, v2
	s_nop 1
	v_cndmask_b32_e32 v1, v3, v5, vcc
	v_mad_u64_u32 v[2:3], s[4:5], v2, v1, v[2:3]
	v_cmp_ne_u32_e32 vcc, v4, v2
	s_and_saveexec_b64 s[4:5], vcc
	s_xor_b64 s[4:5], exec, s[4:5]
	s_cbranch_execz .LBB0_230
	buffer_inv sc1
	v_mov_b32_e32 v0, s3
	v_add_co_u32_e32 v2, vcc, 0x2000, v0
	v_mov_b32_e32 v0, s1
	s_nop 0
	v_addc_co_u32_e32 v3, vcc, 0, v0, vcc
	flat_load_dword v0, v[2:3] offset:1024 sc1
	s_add_u32 s10, s3, 0x2400
	s_addc_u32 s11, s1, 0
	s_waitcnt vmcnt(0) lgkmcnt(0)
	v_cmp_eq_u32_e32 vcc, v0, v1
	s_and_saveexec_b64 s[6:7], vcc
	s_cbranch_execz .LBB0_229
	s_add_u32 s8, s38, 0x1200
	s_addc_u32 s9, s39, 0
	s_mov_b32 s16, 1
	s_mov_b64 s[12:13], 0
	s_branch .LBB0_221

.LBB0_229:
	s_or_b64 exec, exec, s[6:7]
	s_waitcnt vmcnt(0) lgkmcnt(0)
	s_waitcnt vmcnt(0)
.LBB0_230:
	s_andn2_saveexec_b64 s[4:5], s[4:5]
	s_cbranch_execz .LBB0_246
	v_mov_b32_e32 v1, s38
	v_add_co_u32_e32 v2, vcc, 0x4000, v1
	v_mov_b32_e32 v1, s39
	buffer_wbl2 sc1
	buffer_inv sc1
	s_waitcnt vmcnt(0)
	v_addc_co_u32_e32 v3, vcc, 0, v1, vcc
	v_mov_b32_e32 v1, 1
	flat_atomic_add v1, v[2:3], v1 offset:1024 sc0
	v_cvt_f32_u32_e32 v2, v0
	v_sub_u32_e32 v3, 0, v0
	s_add_u32 s4, s38, 0x4500
	s_addc_u32 s5, s39, 0
	v_rcp_iflag_f32_e32 v2, v2
	s_mov_b64 s[8:9], -1
	v_mul_f32_e32 v2, 0x4f7ffffe, v2
	v_cvt_u32_f32_e32 v2, v2
	v_mul_lo_u32 v3, v3, v2
	v_mul_hi_u32 v3, v2, v3
	v_add_u32_e32 v2, v2, v3
	s_waitcnt vmcnt(0) lgkmcnt(0)
	v_mul_hi_u32 v2, v1, v2
	v_mul_lo_u32 v4, v2, v0
	v_add_u32_e32 v3, 1, v1
	v_sub_u32_e32 v1, v1, v4
	v_add_u32_e32 v5, 1, v2
	v_cmp_ge_u32_e32 vcc, v1, v0
	v_sub_u32_e32 v4, v1, v0
	s_nop 0
	v_cndmask_b32_e32 v2, v2, v5, vcc
	v_cndmask_b32_e32 v1, v1, v4, vcc
	v_add_u32_e32 v4, 1, v2
	v_cmp_ge_u32_e32 vcc, v1, v0
	s_nop 1
	v_cndmask_b32_e32 v2, v2, v4, vcc
	v_mad_u64_u32 v[0:1], s[6:7], v0, v2, v[0:1]
	v_cmp_ne_u32_e32 vcc, v3, v0
	v_mov_b64_e32 v[0:1], s[4:5]
	s_and_saveexec_b64 s[6:7], vcc
	s_cbranch_execz .LBB0_243
	v_mov_b64_e32 v[0:1], s[4:5]
	flat_load_dword v0, v[0:1] sc1
	s_mov_b64 s[12:13], 0
	s_waitcnt vmcnt(0) lgkmcnt(0)
	v_cmp_eq_u32_e32 vcc, v0, v2
	s_and_saveexec_b64 s[10:11], vcc
	s_cbranch_execz .LBB0_242
	s_add_u32 s8, s38, 0x1200
	s_addc_u32 s9, s39, 0
	s_mov_b32 s16, 1
	s_branch .LBB0_235

.LBB0_245:
	s_or_b64 exec, exec, s[4:5]
	v_mov_b32_e32 v0, s3
	v_add_co_u32_e32 v0, vcc, 0x2000, v0
	v_mov_b32_e32 v1, s1
	s_nop 0
	v_addc_co_u32_e32 v1, vcc, 0, v1, vcc
	v_mov_b32_e32 v2, 1
	s_waitcnt vmcnt(0) lgkmcnt(0)
	flat_atomic_add v[0:1], v2 offset:1024
	s_waitcnt vmcnt(0)

.LBB0_247:
	s_or_b64 exec, exec, s[4:5]
	v_mov_b32_e32 v0, s28
	v_add_co_u32_e32 v0, vcc, 0x2000, v0
	v_mov_b32_e32 v1, s1
	s_nop 0
	v_addc_co_u32_e32 v1, vcc, 0, v1, vcc
	s_waitcnt vmcnt(0) lgkmcnt(0)
	flat_atomic_add v[0:1], v237 offset:1024
	s_waitcnt vmcnt(0)

.LBB0_486:
	s_lshl_b32 s4, s54, 8
	s_add_u32 s4, s86, s4
	s_addc_u32 s5, s87, 0
	v_mov_b32_e32 v1, s4
	v_add_co_u32_e32 v4, vcc, 0x2000, v1
	v_mov_b32_e32 v1, s5
	s_nop 0
	v_addc_co_u32_e32 v5, vcc, 0, v1, vcc
	flat_atomic_add v1, v[4:5], v237 offset:1024 sc0
	v_cvt_f32_u32_e32 v3, v2
	v_sub_u32_e32 v4, 0, v2
	s_add_u32 s29, s4, 0x1000
	s_addc_u32 s28, s5, 0
	v_rcp_iflag_f32_e32 v3, v3
	s_nop 0
	v_mul_f32_e32 v3, 0x4f7ffffe, v3
	v_cvt_u32_f32_e32 v3, v3
	v_mul_lo_u32 v4, v4, v3
	v_mul_hi_u32 v4, v3, v4
	v_add_u32_e32 v3, v3, v4
	s_waitcnt vmcnt(0) lgkmcnt(0)
	v_mul_hi_u32 v3, v1, v3
	v_mul_lo_u32 v5, v3, v2
	v_add_u32_e32 v4, 1, v1
	v_sub_u32_e32 v1, v1, v5
	v_add_u32_e32 v6, 1, v3
	v_cmp_ge_u32_e32 vcc, v1, v2
	v_sub_u32_e32 v5, v1, v2
	s_nop 0
	v_cndmask_b32_e32 v3, v3, v6, vcc
	v_cndmask_b32_e32 v1, v1, v5, vcc
	v_add_u32_e32 v5, 1, v3
	v_cmp_ge_u32_e32 vcc, v1, v2
	s_nop 1
	v_cndmask_b32_e32 v1, v3, v5, vcc
	v_mad_u64_u32 v[2:3], s[4:5], v2, v1, v[2:3]
	v_cmp_ne_u32_e32 vcc, v4, v2
	s_and_saveexec_b64 s[4:5], vcc
	s_xor_b64 s[4:5], exec, s[4:5]
	s_cbranch_execz .LBB0_499
	buffer_inv sc1
	v_mov_b32_e32 v0, s29
	v_add_co_u32_e32 v2, vcc, 0x2000, v0
	v_mov_b32_e32 v0, s28
	s_nop 0
	v_addc_co_u32_e32 v3, vcc, 0, v0, vcc
	flat_load_dword v0, v[2:3] offset:1024 sc1
	s_add_u32 s8, s29, 0x2400
	s_addc_u32 s9, s28, 0
	s_waitcnt vmcnt(0) lgkmcnt(0)
	v_cmp_eq_u32_e32 vcc, v0, v1
	s_and_saveexec_b64 s[6:7], vcc
	s_cbranch_execz .LBB0_498
	s_add_u32 s10, s86, 0x1200
	s_addc_u32 s11, s87, 0
	s_mov_b32 s30, 1
	s_mov_b64 s[12:13], 0
	s_branch .LBB0_490

.LBB0_499:
	s_andn2_saveexec_b64 s[4:5], s[4:5]
	s_cbranch_execz .LBB0_515
	v_mov_b32_e32 v1, s86
	v_add_co_u32_e32 v2, vcc, 0x4000, v1
	v_mov_b32_e32 v1, s87
	buffer_wbl2 sc1
	buffer_inv sc1
	s_waitcnt vmcnt(0)
	v_addc_co_u32_e32 v3, vcc, 0, v1, vcc
	flat_atomic_add v1, v[2:3], v237 offset:1024 sc0
	v_cvt_f32_u32_e32 v2, v0
	v_sub_u32_e32 v3, 0, v0
	s_add_u32 s6, s86, 0x4500
	s_addc_u32 s7, s87, 0
	v_rcp_iflag_f32_e32 v2, v2
	s_mov_b64 s[10:11], -1
	v_mul_f32_e32 v2, 0x4f7ffffe, v2
	v_cvt_u32_f32_e32 v2, v2
	v_mul_lo_u32 v3, v3, v2
	v_mul_hi_u32 v3, v2, v3
	v_add_u32_e32 v2, v2, v3
	s_waitcnt vmcnt(0) lgkmcnt(0)
	v_mul_hi_u32 v2, v1, v2
	v_mul_lo_u32 v4, v2, v0
	v_add_u32_e32 v3, 1, v1
	v_sub_u32_e32 v1, v1, v4
	v_add_u32_e32 v5, 1, v2
	v_cmp_ge_u32_e32 vcc, v1, v0
	v_sub_u32_e32 v4, v1, v0
	s_nop 0
	v_cndmask_b32_e32 v2, v2, v5, vcc
	v_cndmask_b32_e32 v1, v1, v4, vcc
	v_add_u32_e32 v4, 1, v2
	v_cmp_ge_u32_e32 vcc, v1, v0
	s_nop 1
	v_cndmask_b32_e32 v2, v2, v4, vcc
	v_mad_u64_u32 v[0:1], s[8:9], v0, v2, v[0:1]
	v_cmp_ne_u32_e32 vcc, v3, v0
	v_mov_b64_e32 v[0:1], s[6:7]
	s_and_saveexec_b64 s[8:9], vcc
	s_cbranch_execz .LBB0_512
	v_mov_b64_e32 v[0:1], s[6:7]
	flat_load_dword v0, v[0:1] sc1
	s_mov_b64 s[14:15], 0
	s_waitcnt vmcnt(0) lgkmcnt(0)
	v_cmp_eq_u32_e32 vcc, v0, v2
	s_and_saveexec_b64 s[12:13], vcc
	s_cbranch_execz .LBB0_511
	s_add_u32 s10, s86, 0x1200
	s_addc_u32 s11, s87, 0
	s_mov_b32 s30, 1
	s_branch .LBB0_504

.LBB0_514:
	s_or_b64 exec, exec, s[6:7]
	v_mov_b32_e32 v0, s29
	v_add_co_u32_e32 v0, vcc, 0x2000, v0
	v_mov_b32_e32 v1, s28
	s_nop 0
	v_addc_co_u32_e32 v1, vcc, 0, v1, vcc
	s_waitcnt vmcnt(0) lgkmcnt(0)
	flat_atomic_add v[0:1], v237 offset:1024
	s_waitcnt vmcnt(0)

.LBB0_676:
	s_andn2_saveexec_b64 s[4:5], s[4:5]
	s_cbranch_execz .LBB0_692
	v_mov_b32_e32 v1, s86
	v_add_co_u32_e32 v2, vcc, 0x4000, v1
	v_mov_b32_e32 v1, s87
	buffer_wbl2 sc1
	buffer_inv sc1
	s_waitcnt vmcnt(0)
	v_addc_co_u32_e32 v3, vcc, 0, v1, vcc
	flat_atomic_add v1, v[2:3], v237 offset:1024 sc0
	v_cvt_f32_u32_e32 v2, v0
	v_sub_u32_e32 v3, 0, v0
	s_mov_b64 s[8:9], -1
	v_rcp_iflag_f32_e32 v2, v2
	s_nop 0
	v_mul_f32_e32 v2, 0x4f7ffffe, v2
	v_cvt_u32_f32_e32 v2, v2
	v_mul_lo_u32 v3, v3, v2
	v_mul_hi_u32 v3, v2, v3
	v_add_u32_e32 v2, v2, v3
	s_waitcnt vmcnt(0) lgkmcnt(0)
	v_mul_hi_u32 v2, v1, v2
	v_mul_lo_u32 v3, v2, v0
	v_sub_u32_e32 v3, v1, v3
	v_cmp_ge_u32_e32 vcc, v3, v0
	v_add_u32_e32 v4, 1, v2
	s_nop 0
	v_cndmask_b32_e32 v2, v2, v4, vcc
	v_sub_u32_e32 v4, v3, v0
	v_cndmask_b32_e32 v3, v3, v4, vcc
	v_cmp_ge_u32_e32 vcc, v3, v0
	v_add_u32_e32 v3, 1, v2
	s_nop 0
	v_cndmask_b32_e32 v2, v2, v3, vcc
	v_add_u32_e32 v3, 1, v1
	v_mad_u64_u32 v[0:1], s[4:5], v0, v2, v[0:1]
	s_add_u32 s4, s86, 0x4500
	s_addc_u32 s5, s87, 0
	v_cmp_ne_u32_e32 vcc, v3, v0
	v_mov_b64_e32 v[0:1], s[4:5]
	s_and_saveexec_b64 s[6:7], vcc
	s_cbranch_execz .LBB0_689
	v_mov_b64_e32 v[0:1], s[4:5]
	flat_load_dword v0, v[0:1] sc1
	s_mov_b64 s[12:13], 0
	s_waitcnt vmcnt(0) lgkmcnt(0)
	v_cmp_eq_u32_e32 vcc, v0, v2
	s_and_saveexec_b64 s[10:11], vcc
	s_cbranch_execz .LBB0_688
	s_add_u32 s8, s86, 0x1200
	s_addc_u32 s9, s87, 0
	s_mov_b32 s26, 1
	s_branch .LBB0_681

.LBB0_691:
	s_or_b64 exec, exec, s[4:5]
	v_mov_b32_e32 v0, s29
	v_add_co_u32_e32 v0, vcc, 0x2000, v0
	v_mov_b32_e32 v1, s28
	s_nop 0
	v_addc_co_u32_e32 v1, vcc, 0, v1, vcc
	s_waitcnt vmcnt(0) lgkmcnt(0)
	flat_atomic_add v[0:1], v237 offset:1024
	s_waitcnt vmcnt(0)

.LBB0_897:
	s_lshl_b32 s6, s68, 8
	s_add_u32 s6, s88, s6
	s_addc_u32 s7, s89, 0
	v_mov_b32_e32 v1, s6
	v_add_co_u32_e32 v4, vcc, 0x2000, v1
	v_mov_b32_e32 v1, s7
	s_nop 0
	v_addc_co_u32_e32 v5, vcc, 0, v1, vcc
	flat_atomic_add v3, v[4:5], v237 offset:1024 sc0
	v_cvt_f32_u32_e32 v1, v2
	v_sub_u32_e32 v4, 0, v2
	s_add_u32 s31, s6, 0x1000
	s_addc_u32 s30, s7, 0
	v_rcp_iflag_f32_e32 v1, v1
	s_nop 0
	v_mul_f32_e32 v1, 0x4f7ffffe, v1
	v_cvt_u32_f32_e32 v1, v1
	v_mul_lo_u32 v4, v4, v1
	v_mul_hi_u32 v4, v1, v4
	v_add_u32_e32 v1, v1, v4
	s_waitcnt vmcnt(0) lgkmcnt(0)
	v_mul_hi_u32 v1, v3, v1
	v_mul_lo_u32 v4, v1, v2
	v_sub_u32_e32 v4, v3, v4
	v_cmp_ge_u32_e32 vcc, v4, v2
	v_add_u32_e32 v5, 1, v1
	s_nop 0
	v_cndmask_b32_e32 v1, v1, v5, vcc
	v_sub_u32_e32 v5, v4, v2
	v_cndmask_b32_e32 v4, v4, v5, vcc
	v_cmp_ge_u32_e32 vcc, v4, v2
	v_add_u32_e32 v4, 1, v1
	s_nop 0
	v_cndmask_b32_e32 v1, v1, v4, vcc
	v_add_u32_e32 v4, 1, v3
	v_mad_u64_u32 v[2:3], s[6:7], v2, v1, v[2:3]
	v_cmp_ne_u32_e32 vcc, v4, v2
	s_and_saveexec_b64 s[6:7], vcc
	s_xor_b64 s[6:7], exec, s[6:7]
	s_cbranch_execz .LBB0_910
	buffer_inv sc1
	v_mov_b32_e32 v0, s31
	v_add_co_u32_e32 v2, vcc, 0x2000, v0
	v_mov_b32_e32 v0, s30
	s_nop 0
	v_addc_co_u32_e32 v3, vcc, 0, v0, vcc
	flat_load_dword v0, v[2:3] offset:1024 sc1
	s_add_u32 s10, s31, 0x2400
	s_addc_u32 s11, s30, 0
	s_waitcnt vmcnt(0) lgkmcnt(0)
	v_cmp_eq_u32_e32 vcc, v0, v1
	s_and_saveexec_b64 s[8:9], vcc
	s_cbranch_execz .LBB0_909
	s_add_u32 s12, s88, 0x1200
	s_addc_u32 s13, s89, 0
	s_mov_b32 s34, 1
	s_mov_b64 s[14:15], 0
	s_branch .LBB0_901

.LBB0_909:
	s_or_b64 exec, exec, s[8:9]
	s_waitcnt vmcnt(0) lgkmcnt(0)
	s_waitcnt vmcnt(0)
.LBB0_910:
	s_andn2_saveexec_b64 s[6:7], s[6:7]
	s_cbranch_execz .LBB0_926
	v_mov_b32_e32 v1, s88
	v_add_co_u32_e32 v2, vcc, 0x4000, v1
	v_mov_b32_e32 v1, s89
	buffer_wbl2 sc1
	buffer_inv sc1
	s_waitcnt vmcnt(0)
	v_addc_co_u32_e32 v3, vcc, 0, v1, vcc
	flat_atomic_add v1, v[2:3], v237 offset:1024 sc0
	v_cvt_f32_u32_e32 v2, v0
	v_sub_u32_e32 v3, 0, v0
	s_mov_b64 s[10:11], -1
	v_rcp_iflag_f32_e32 v2, v2
	s_nop 0
	v_mul_f32_e32 v2, 0x4f7ffffe, v2
	v_cvt_u32_f32_e32 v2, v2
	v_mul_lo_u32 v3, v3, v2
	v_mul_hi_u32 v3, v2, v3
	v_add_u32_e32 v2, v2, v3
	s_waitcnt vmcnt(0) lgkmcnt(0)
	v_mul_hi_u32 v2, v1, v2
	v_mul_lo_u32 v3, v2, v0
	v_sub_u32_e32 v3, v1, v3
	v_cmp_ge_u32_e32 vcc, v3, v0
	v_add_u32_e32 v4, 1, v2
	s_nop 0
	v_cndmask_b32_e32 v2, v2, v4, vcc
	v_sub_u32_e32 v4, v3, v0
	v_cndmask_b32_e32 v3, v3, v4, vcc
	v_cmp_ge_u32_e32 vcc, v3, v0
	v_add_u32_e32 v3, 1, v2
	s_nop 0
	v_cndmask_b32_e32 v2, v2, v3, vcc
	v_add_u32_e32 v3, 1, v1
	v_mad_u64_u32 v[0:1], s[6:7], v0, v2, v[0:1]
	s_add_u32 s6, s88, 0x4500
	s_addc_u32 s7, s89, 0
	v_cmp_ne_u32_e32 vcc, v3, v0
	v_mov_b64_e32 v[0:1], s[6:7]
	s_and_saveexec_b64 s[8:9], vcc
	s_cbranch_execz .LBB0_923
	v_mov_b64_e32 v[0:1], s[6:7]
	flat_load_dword v0, v[0:1] sc1
	s_mov_b64 s[14:15], 0
	s_waitcnt vmcnt(0) lgkmcnt(0)
	v_cmp_eq_u32_e32 vcc, v0, v2
	s_and_saveexec_b64 s[12:13], vcc
	s_cbranch_execz .LBB0_922
	s_add_u32 s10, s88, 0x1200
	s_addc_u32 s11, s89, 0
	s_mov_b32 s28, 1
	s_branch .LBB0_915

.LBB0_925:
	s_or_b64 exec, exec, s[6:7]
	v_mov_b32_e32 v0, s31
	v_add_co_u32_e32 v0, vcc, 0x2000, v0
	v_mov_b32_e32 v1, s30
	s_nop 0
	v_addc_co_u32_e32 v1, vcc, 0, v1, vcc
	s_waitcnt vmcnt(0) lgkmcnt(0)
	flat_atomic_add v[0:1], v237 offset:1024
	s_waitcnt vmcnt(0)

.LBB0_970:
	s_andn2_saveexec_b64 s[6:7], s[6:7]
	s_cbranch_execz .LBB0_986
	v_mov_b32_e32 v1, s88
	v_add_co_u32_e32 v2, vcc, 0x4000, v1
	v_mov_b32_e32 v1, s89
	buffer_wbl2 sc1
	buffer_inv sc1
	s_waitcnt vmcnt(0)
	v_addc_co_u32_e32 v3, vcc, 0, v1, vcc
	flat_atomic_add v1, v[2:3], v237 offset:1024 sc0
	v_cvt_f32_u32_e32 v2, v0
	v_sub_u32_e32 v3, 0, v0
	s_mov_b64 s[12:13], -1
	v_rcp_iflag_f32_e32 v2, v2
	s_nop 0
	v_mul_f32_e32 v2, 0x4f7ffffe, v2
	v_cvt_u32_f32_e32 v2, v2
	v_mul_lo_u32 v3, v3, v2
	v_mul_hi_u32 v3, v2, v3
	v_add_u32_e32 v2, v2, v3
	s_waitcnt vmcnt(0) lgkmcnt(0)
	v_mul_hi_u32 v2, v1, v2
	v_mul_lo_u32 v3, v2, v0
	v_sub_u32_e32 v3, v1, v3
	v_cmp_ge_u32_e32 vcc, v3, v0
	v_add_u32_e32 v4, 1, v2
	s_nop 0
	v_cndmask_b32_e32 v2, v2, v4, vcc
	v_sub_u32_e32 v4, v3, v0
	v_cndmask_b32_e32 v3, v3, v4, vcc
	v_cmp_ge_u32_e32 vcc, v3, v0
	v_add_u32_e32 v3, 1, v2
	s_nop 0
	v_cndmask_b32_e32 v2, v2, v3, vcc
	v_add_u32_e32 v3, 1, v1
	v_mad_u64_u32 v[0:1], s[8:9], v0, v2, v[0:1]
	s_add_u32 s8, s88, 0x4500
	s_addc_u32 s9, s89, 0
	v_cmp_ne_u32_e32 vcc, v3, v0
	v_mov_b64_e32 v[0:1], s[8:9]
	s_and_saveexec_b64 s[10:11], vcc
	s_cbranch_execz .LBB0_983
	v_mov_b64_e32 v[0:1], s[8:9]
	flat_load_dword v0, v[0:1] sc1
	s_mov_b64 s[18:19], 0
	s_waitcnt vmcnt(0) lgkmcnt(0)
	v_cmp_eq_u32_e32 vcc, v0, v2
	s_and_saveexec_b64 s[14:15], vcc
	s_cbranch_execz .LBB0_982
	s_add_u32 s12, s88, 0x1200
	s_addc_u32 s13, s89, 0
	s_mov_b32 s34, 1
	s_branch .LBB0_975

.LBB0_985:
	s_or_b64 exec, exec, s[8:9]
	v_mov_b32_e32 v0, s31
	v_add_co_u32_e32 v0, vcc, 0x2000, v0
	v_mov_b32_e32 v1, s30
	s_nop 0
	v_addc_co_u32_e32 v1, vcc, 0, v1, vcc
	s_waitcnt vmcnt(0) lgkmcnt(0)
	flat_atomic_add v[0:1], v237 offset:1024
	s_waitcnt vmcnt(0)

.LBB0_1042:
	s_lshl_b32 s1, s1, 8
	s_add_u32 s1, s86, s1
	s_addc_u32 s4, s87, 0
	v_mov_b32_e32 v1, s1
	v_add_co_u32_e32 v4, vcc, 0x2000, v1
	v_mov_b32_e32 v1, s4
	s_nop 0
	v_addc_co_u32_e32 v5, vcc, 0, v1, vcc
	flat_atomic_add v1, v[4:5], v237 offset:1024 sc0
	v_cvt_f32_u32_e32 v3, v2
	v_sub_u32_e32 v4, 0, v2
	s_add_u32 s28, s1, 0x1000
	s_addc_u32 s1, s4, 0
	v_rcp_iflag_f32_e32 v3, v3
	s_nop 0
	v_mul_f32_e32 v3, 0x4f7ffffe, v3
	v_cvt_u32_f32_e32 v3, v3
	v_mul_lo_u32 v4, v4, v3
	v_mul_hi_u32 v4, v3, v4
	v_add_u32_e32 v3, v3, v4
	s_waitcnt vmcnt(0) lgkmcnt(0)
	v_mul_hi_u32 v3, v1, v3
	v_mul_lo_u32 v5, v3, v2
	v_add_u32_e32 v4, 1, v1
	v_sub_u32_e32 v1, v1, v5
	v_add_u32_e32 v6, 1, v3
	v_cmp_ge_u32_e32 vcc, v1, v2
	v_sub_u32_e32 v5, v1, v2
	s_nop 0
	v_cndmask_b32_e32 v3, v3, v6, vcc
	v_cndmask_b32_e32 v1, v1, v5, vcc
	v_add_u32_e32 v5, 1, v3
	v_cmp_ge_u32_e32 vcc, v1, v2
	s_nop 1
	v_cndmask_b32_e32 v1, v3, v5, vcc
	v_mad_u64_u32 v[2:3], s[4:5], v2, v1, v[2:3]
	v_cmp_ne_u32_e32 vcc, v4, v2
	s_and_saveexec_b64 s[4:5], vcc
	s_xor_b64 s[4:5], exec, s[4:5]
	s_cbranch_execz .LBB0_1055
	buffer_inv sc1
	v_mov_b32_e32 v0, s28
	v_add_co_u32_e32 v2, vcc, 0x2000, v0
	v_mov_b32_e32 v0, s1
	s_nop 0
	v_addc_co_u32_e32 v3, vcc, 0, v0, vcc
	flat_load_dword v0, v[2:3] offset:1024 sc1
	s_add_u32 s8, s28, 0x2400
	s_addc_u32 s9, s1, 0
	s_waitcnt vmcnt(0) lgkmcnt(0)
	v_cmp_eq_u32_e32 vcc, v0, v1
	s_and_saveexec_b64 s[6:7], vcc
	s_cbranch_execz .LBB0_1054
	s_add_u32 s10, s86, 0x1200
	s_addc_u32 s11, s87, 0
	s_mov_b32 s29, 1
	s_mov_b64 s[12:13], 0
	s_branch .LBB0_1046

.LBB0_1055:
	s_andn2_saveexec_b64 s[4:5], s[4:5]
	s_cbranch_execz .LBB0_248
	v_mov_b32_e32 v1, s86
	v_add_co_u32_e32 v2, vcc, 0x4000, v1
	v_mov_b32_e32 v1, s87
	buffer_wbl2 sc1
	buffer_inv sc1
	s_waitcnt vmcnt(0)
	v_addc_co_u32_e32 v3, vcc, 0, v1, vcc
	flat_atomic_add v1, v[2:3], v237 offset:1024 sc0
	v_cvt_f32_u32_e32 v2, v0
	v_sub_u32_e32 v3, 0, v0
	s_add_u32 s4, s86, 0x4500
	s_addc_u32 s5, s87, 0
	v_rcp_iflag_f32_e32 v2, v2
	s_mov_b64 s[8:9], -1
	v_mul_f32_e32 v2, 0x4f7ffffe, v2
	v_cvt_u32_f32_e32 v2, v2
	v_mul_lo_u32 v3, v3, v2
	v_mul_hi_u32 v3, v2, v3
	v_add_u32_e32 v2, v2, v3
	s_waitcnt vmcnt(0) lgkmcnt(0)
	v_mul_hi_u32 v2, v1, v2
	v_mul_lo_u32 v4, v2, v0
	v_add_u32_e32 v3, 1, v1
	v_sub_u32_e32 v1, v1, v4
	v_add_u32_e32 v5, 1, v2
	v_cmp_ge_u32_e32 vcc, v1, v0
	v_sub_u32_e32 v4, v1, v0
	s_nop 0
	v_cndmask_b32_e32 v2, v2, v5, vcc
	v_cndmask_b32_e32 v1, v1, v4, vcc
	v_add_u32_e32 v4, 1, v2
	v_cmp_ge_u32_e32 vcc, v1, v0
	s_nop 1
	v_cndmask_b32_e32 v2, v2, v4, vcc
	v_mad_u64_u32 v[0:1], s[6:7], v0, v2, v[0:1]
	v_cmp_ne_u32_e32 vcc, v3, v0
	v_mov_b64_e32 v[0:1], s[4:5]
	s_and_saveexec_b64 s[6:7], vcc
	s_cbranch_execz .LBB0_1068
	v_mov_b64_e32 v[0:1], s[4:5]
	flat_load_dword v0, v[0:1] sc1
	s_mov_b64 s[12:13], 0
	s_waitcnt vmcnt(0) lgkmcnt(0)
	v_cmp_eq_u32_e32 vcc, v0, v2
	s_and_saveexec_b64 s[10:11], vcc
	s_cbranch_execz .LBB0_1067
	s_add_u32 s8, s86, 0x1200
	s_addc_u32 s9, s87, 0
	s_mov_b32 s26, 1
	s_branch .LBB0_1060
